# FF1 (prompt panels) epilogue rewritten with the same prefetch-ring structure as G1
# baseline (speedup 1.0000x reference)
.LBB0_1233:
	v_lshl_add_u32 v182, s47, 8, v160
	v_lshl_or_b32 v171, s48, 8, v162
	v_lshlrev_b32_e32 v172, 6, v182
	v_mov_b32_e32 v173, 0
	v_lshl_add_u64 v[172:173], v[150:151], 0, v[172:173]
	s_mov_b32 s34, 0x2000
	s_mov_b32 s35, 0
	v_readlane_b32 s23, v243, 57
	global_load_dwordx4 v[198:201], v[172:173], off
	global_load_dwordx4 v[202:205], v[172:173], off offset:1024
	global_load_dwordx4 v[206:209], v[172:173], off offset:2048
	global_load_dwordx4 v[210:213], v[172:173], off offset:3072
	v_lshl_add_u64 v[172:173], v[172:173], 0, s[34:35]
	global_load_dwordx4 v[224:227], v[172:173], off
	global_load_dwordx4 v[228:231], v[172:173], off offset:1024
	global_load_dwordx4 v[232:235], v[172:173], off offset:2048
	global_load_dwordx4 v[236:239], v[172:173], off offset:3072
	v_lshlrev_b32_e32 v183, 2, v171
	v_lshlrev_b32_e32 v171, 1, v171
	v_lshl_add_u32 v197, v182, 13, v171
	v_xor_b32_e32 v194, 16, v221
	v_lshlrev_b32_e32 v194, 2, v194
	v_xor_b32_e32 v196, 32, v221
	v_lshlrev_b32_e32 v196, 2, v196
	v_cmp_gt_i32_e32 vcc, s33, v182
	v_add_u32_e32 v167, s44, v182
	v_add_u32_e32 v168, s45, v182
	v_cndmask_b32_e32 v167, v167, v168, vcc
	v_cmp_gt_i32_e32 vcc, s90, v167
	v_add_u32_e32 v168, 0xffffc000, v167
	v_lshrrev_b32_e32 v168, 3, v168
	v_ashrrev_i32_e32 v169, 11, v167
	v_add_u32_e32 v168, 8, v168
	v_cndmask_b32_e32 v167, v168, v169, vcc
	v_lshl_add_u32 v171, v167, 14, v183
	global_load_dwordx4 v[104:107], v171, s[14:15]
	global_load_dwordx4 v[112:115], v171, s[14:15] offset:16
	global_load_dwordx4 v[124:127], v171, s[14:15] offset:512
	global_load_dwordx4 v[120:123], v171, s[14:15] offset:528
	s_waitcnt vmcnt(4)
	v_add_f32_e32 v174, v198, v199
	v_add_f32_e32 v186, v200, v201
	v_add_f32_e32 v175, v202, v203
	v_add_f32_e32 v187, v204, v205
	v_add_f32_e32 v176, v206, v207
	v_add_f32_e32 v188, v208, v209
	v_add_f32_e32 v177, v210, v211
	v_add_f32_e32 v189, v212, v213
	v_add_f32_e32 v178, v224, v225
	v_add_f32_e32 v190, v226, v227
	v_add_f32_e32 v179, v228, v229
	v_add_f32_e32 v191, v230, v231
	v_add_f32_e32 v180, v232, v233
	v_add_f32_e32 v192, v234, v235
	v_add_f32_e32 v181, v236, v237
	v_add_f32_e32 v193, v238, v239
	v_add_f32_e32 v174, v174, v186
	v_add_f32_e32 v175, v175, v187
	v_add_f32_e32 v176, v176, v188
	v_add_f32_e32 v177, v177, v189
	v_add_f32_e32 v178, v178, v190
	v_add_f32_e32 v179, v179, v191
	v_add_f32_e32 v180, v180, v192
	v_add_f32_e32 v181, v181, v193
	ds_bpermute_b32 v186, v194, v174
	ds_bpermute_b32 v187, v194, v175
	ds_bpermute_b32 v188, v194, v176
	ds_bpermute_b32 v189, v194, v177
	ds_bpermute_b32 v190, v194, v178
	ds_bpermute_b32 v191, v194, v179
	ds_bpermute_b32 v192, v194, v180
	ds_bpermute_b32 v193, v194, v181
	v_or_b32_e32 v170, 16, v182
	v_cmp_gt_i32_e32 vcc, s33, v170
	v_add_u32_e32 v167, s44, v170
	v_add_u32_e32 v168, s45, v170
	v_cndmask_b32_e32 v167, v167, v168, vcc
	v_cmp_gt_i32_e32 vcc, s90, v167
	v_add_u32_e32 v168, 0xffffc000, v167
	v_lshrrev_b32_e32 v168, 3, v168
	v_ashrrev_i32_e32 v169, 11, v167
	v_add_u32_e32 v168, 8, v168
	v_cndmask_b32_e32 v167, v168, v169, vcc
	v_lshl_add_u32 v171, v167, 14, v183
	global_load_dwordx4 v[198:201], v171, s[14:15]
	global_load_dwordx4 v[202:205], v171, s[14:15] offset:16
	global_load_dwordx4 v[206:209], v171, s[14:15] offset:512
	global_load_dwordx4 v[210:213], v171, s[14:15] offset:528
	s_waitcnt lgkmcnt(0)
	v_add_f32_e32 v174, v174, v186
	v_add_f32_e32 v175, v175, v187
	v_add_f32_e32 v176, v176, v188
	v_add_f32_e32 v177, v177, v189
	v_add_f32_e32 v178, v178, v190
	v_add_f32_e32 v179, v179, v191
	v_add_f32_e32 v180, v180, v192
	v_add_f32_e32 v181, v181, v193
	ds_bpermute_b32 v186, v196, v174
	ds_bpermute_b32 v187, v196, v175
	ds_bpermute_b32 v188, v196, v176
	ds_bpermute_b32 v189, v196, v177
	ds_bpermute_b32 v190, v196, v178
	ds_bpermute_b32 v191, v196, v179
	ds_bpermute_b32 v192, v196, v180
	ds_bpermute_b32 v193, v196, v181
	v_or_b32_e32 v170, 32, v182
	v_cmp_gt_i32_e32 vcc, s33, v170
	v_add_u32_e32 v167, s44, v170
	v_add_u32_e32 v168, s45, v170
	v_cndmask_b32_e32 v167, v167, v168, vcc
	v_cmp_gt_i32_e32 vcc, s90, v167
	v_add_u32_e32 v168, 0xffffc000, v167
	v_lshrrev_b32_e32 v168, 3, v168
	v_ashrrev_i32_e32 v169, 11, v167
	v_add_u32_e32 v168, 8, v168
	v_cndmask_b32_e32 v167, v168, v169, vcc
	v_lshl_add_u32 v171, v167, 14, v183
	global_load_dwordx4 v[224:227], v171, s[14:15]
	global_load_dwordx4 v[228:231], v171, s[14:15] offset:16
	global_load_dwordx4 v[232:235], v171, s[14:15] offset:512
	global_load_dwordx4 v[236:239], v171, s[14:15] offset:528
	s_waitcnt lgkmcnt(0)
	v_add_f32_e32 v174, v174, v186
	v_add_f32_e32 v175, v175, v187
	v_add_f32_e32 v176, v176, v188
	v_add_f32_e32 v177, v177, v189
	v_add_f32_e32 v178, v178, v190
	v_add_f32_e32 v179, v179, v191
	v_add_f32_e32 v180, v180, v192
	v_add_f32_e32 v181, v181, v193
	v_fmamk_f32 v174, v174, 0x3a800000, v216
	v_fmamk_f32 v175, v175, 0x3a800000, v216
	v_fmamk_f32 v176, v176, 0x3a800000, v216
	v_fmamk_f32 v177, v177, 0x3a800000, v216
	v_fmamk_f32 v178, v178, 0x3a800000, v216
	v_fmamk_f32 v179, v179, 0x3a800000, v216
	v_fmamk_f32 v180, v180, 0x3a800000, v216
	v_fmamk_f32 v181, v181, 0x3a800000, v216
	v_rsq_f32_e32 v174, v174
	v_rsq_f32_e32 v175, v175
	v_rsq_f32_e32 v176, v176
	v_rsq_f32_e32 v177, v177
	v_rsq_f32_e32 v178, v178
	v_rsq_f32_e32 v179, v179
	v_rsq_f32_e32 v180, v180
	v_rsq_f32_e32 v181, v181
	s_nop 0
	s_waitcnt vmcnt(8)
	v_pk_fma_f32 v[142:143], v[142:143], v[174:175], v[106:107] op_sel_hi:[1,0,1]
	v_pk_fma_f32 v[140:141], v[140:141], v[174:175], v[104:105] op_sel_hi:[1,0,1]
	v_pk_fma_f32 v[138:139], v[138:139], v[174:175], v[114:115] op_sel_hi:[1,0,1]
	v_pk_fma_f32 v[136:137], v[136:137], v[174:175], v[112:113] op_sel_hi:[1,0,1]
	v_pk_fma_f32 v[134:135], v[134:135], v[174:175], v[126:127] op_sel_hi:[1,0,1]
	v_pk_fma_f32 v[132:133], v[132:133], v[174:175], v[124:125] op_sel_hi:[1,0,1]
	v_pk_fma_f32 v[130:131], v[130:131], v[174:175], v[122:123] op_sel_hi:[1,0,1]
	v_pk_fma_f32 v[128:129], v[128:129], v[174:175], v[120:121] op_sel_hi:[1,0,1]
	v_max_f32_e32 v140, 0, v140
	v_max_f32_e32 v141, 0, v141
	v_max_f32_e32 v142, 0, v142
	v_max_f32_e32 v143, 0, v143
	v_max_f32_e32 v136, 0, v136
	v_max_f32_e32 v137, 0, v137
	v_max_f32_e32 v138, 0, v138
	v_max_f32_e32 v139, 0, v139
	v_mul_f32_e32 v140, v140, v140
	v_mul_f32_e32 v141, v141, v141
	v_mul_f32_e32 v142, v142, v142
	v_mul_f32_e32 v143, v143, v143
	v_mul_f32_e32 v136, v136, v136
	v_mul_f32_e32 v137, v137, v137
	v_mul_f32_e32 v138, v138, v138
	v_mul_f32_e32 v139, v139, v139
	v_cvt_pk_bf16_f32 v140, v140, v141
	v_cvt_pk_bf16_f32 v141, v142, v143
	v_cvt_pk_bf16_f32 v142, v136, v137
	v_cvt_pk_bf16_f32 v143, v138, v139
	global_store_dwordx4 v197, v[140:143], s[12:13]
	v_max_f32_e32 v132, 0, v132
	v_max_f32_e32 v133, 0, v133
	v_max_f32_e32 v134, 0, v134
	v_max_f32_e32 v135, 0, v135
	v_max_f32_e32 v128, 0, v128
	v_max_f32_e32 v129, 0, v129
	v_max_f32_e32 v130, 0, v130
	v_max_f32_e32 v131, 0, v131
	v_mul_f32_e32 v132, v132, v132
	v_mul_f32_e32 v133, v133, v133
	v_mul_f32_e32 v134, v134, v134
	v_mul_f32_e32 v135, v135, v135
	v_mul_f32_e32 v128, v128, v128
	v_mul_f32_e32 v129, v129, v129
	v_mul_f32_e32 v130, v130, v130
	v_mul_f32_e32 v131, v131, v131
	v_cvt_pk_bf16_f32 v132, v132, v133
	v_cvt_pk_bf16_f32 v133, v134, v135
	v_cvt_pk_bf16_f32 v134, v128, v129
	v_cvt_pk_bf16_f32 v135, v130, v131
	global_store_dwordx4 v197, v[132:135], s[12:13] offset:256
	v_add_u32_e32 v240, 0x20000, v197
	v_or_b32_e32 v170, 48, v182
	v_cmp_gt_i32_e32 vcc, s33, v170
	v_add_u32_e32 v167, s44, v170
	v_add_u32_e32 v168, s45, v170
	v_cndmask_b32_e32 v167, v167, v168, vcc
	v_cmp_gt_i32_e32 vcc, s90, v167
	v_add_u32_e32 v168, 0xffffc000, v167
	v_lshrrev_b32_e32 v168, 3, v168
	v_ashrrev_i32_e32 v169, 11, v167
	v_add_u32_e32 v168, 8, v168
	v_cndmask_b32_e32 v167, v168, v169, vcc
	v_lshl_add_u32 v171, v167, 14, v183
	global_load_dwordx4 v[104:107], v171, s[14:15]
	global_load_dwordx4 v[112:115], v171, s[14:15] offset:16
	global_load_dwordx4 v[124:127], v171, s[14:15] offset:512
	global_load_dwordx4 v[120:123], v171, s[14:15] offset:528
	s_waitcnt vmcnt(10)
	v_pk_fma_f32 v[118:119], v[118:119], v[174:175], v[200:201] op_sel:[0,1,0] op_sel_hi:[1,1,1]
	v_pk_fma_f32 v[116:117], v[116:117], v[174:175], v[198:199] op_sel:[0,1,0] op_sel_hi:[1,1,1]
	v_pk_fma_f32 v[110:111], v[110:111], v[174:175], v[204:205] op_sel:[0,1,0] op_sel_hi:[1,1,1]
	v_pk_fma_f32 v[108:109], v[108:109], v[174:175], v[202:203] op_sel:[0,1,0] op_sel_hi:[1,1,1]
	v_pk_fma_f32 v[102:103], v[102:103], v[174:175], v[208:209] op_sel:[0,1,0] op_sel_hi:[1,1,1]
	v_pk_fma_f32 v[100:101], v[100:101], v[174:175], v[206:207] op_sel:[0,1,0] op_sel_hi:[1,1,1]
	v_pk_fma_f32 v[98:99], v[98:99], v[174:175], v[212:213] op_sel:[0,1,0] op_sel_hi:[1,1,1]
	v_pk_fma_f32 v[96:97], v[96:97], v[174:175], v[210:211] op_sel:[0,1,0] op_sel_hi:[1,1,1]
	v_max_f32_e32 v116, 0, v116
	v_max_f32_e32 v117, 0, v117
	v_max_f32_e32 v118, 0, v118
	v_max_f32_e32 v119, 0, v119
	v_max_f32_e32 v108, 0, v108
	v_max_f32_e32 v109, 0, v109
	v_max_f32_e32 v110, 0, v110
	v_max_f32_e32 v111, 0, v111
	v_mul_f32_e32 v116, v116, v116
	v_mul_f32_e32 v117, v117, v117
	v_mul_f32_e32 v118, v118, v118
	v_mul_f32_e32 v119, v119, v119
	v_mul_f32_e32 v108, v108, v108
	v_mul_f32_e32 v109, v109, v109
	v_mul_f32_e32 v110, v110, v110
	v_mul_f32_e32 v111, v111, v111
	v_cvt_pk_bf16_f32 v116, v116, v117
	v_cvt_pk_bf16_f32 v117, v118, v119
	v_cvt_pk_bf16_f32 v118, v108, v109
	v_cvt_pk_bf16_f32 v119, v110, v111
	global_store_dwordx4 v240, v[116:119], s[12:13]
	v_max_f32_e32 v100, 0, v100
	v_max_f32_e32 v101, 0, v101
	v_max_f32_e32 v102, 0, v102
	v_max_f32_e32 v103, 0, v103
	v_max_f32_e32 v96, 0, v96
	v_max_f32_e32 v97, 0, v97
	v_max_f32_e32 v98, 0, v98
	v_max_f32_e32 v99, 0, v99
	v_mul_f32_e32 v100, v100, v100
	v_mul_f32_e32 v101, v101, v101
	v_mul_f32_e32 v102, v102, v102
	v_mul_f32_e32 v103, v103, v103
	v_mul_f32_e32 v96, v96, v96
	v_mul_f32_e32 v97, v97, v97
	v_mul_f32_e32 v98, v98, v98
	v_mul_f32_e32 v99, v99, v99
	v_cvt_pk_bf16_f32 v100, v100, v101
	v_cvt_pk_bf16_f32 v101, v102, v103
	v_cvt_pk_bf16_f32 v102, v96, v97
	v_cvt_pk_bf16_f32 v103, v98, v99
	global_store_dwordx4 v240, v[100:103], s[12:13] offset:256
	v_add_u32_e32 v197, 0x20000, v240
	v_add_u32_e32 v170, 0x80, v182
	v_cmp_gt_i32_e32 vcc, s33, v170
	v_add_u32_e32 v167, s44, v170
	v_add_u32_e32 v168, s45, v170
	v_cndmask_b32_e32 v167, v167, v168, vcc
	v_cmp_gt_i32_e32 vcc, s90, v167
	v_add_u32_e32 v168, 0xffffc000, v167
	v_lshrrev_b32_e32 v168, 3, v168
	v_ashrrev_i32_e32 v169, 11, v167
	v_add_u32_e32 v168, 8, v168
	v_cndmask_b32_e32 v167, v168, v169, vcc
	v_lshl_add_u32 v171, v167, 14, v183
	global_load_dwordx4 v[198:201], v171, s[14:15]
	global_load_dwordx4 v[202:205], v171, s[14:15] offset:16
	global_load_dwordx4 v[206:209], v171, s[14:15] offset:512
	global_load_dwordx4 v[210:213], v171, s[14:15] offset:528
	s_waitcnt vmcnt(12)
	v_pk_fma_f32 v[94:95], v[94:95], v[176:177], v[226:227] op_sel_hi:[1,0,1]
	v_pk_fma_f32 v[92:93], v[92:93], v[176:177], v[224:225] op_sel_hi:[1,0,1]
	v_pk_fma_f32 v[90:91], v[90:91], v[176:177], v[230:231] op_sel_hi:[1,0,1]
	v_pk_fma_f32 v[88:89], v[88:89], v[176:177], v[228:229] op_sel_hi:[1,0,1]
	v_pk_fma_f32 v[86:87], v[86:87], v[176:177], v[234:235] op_sel_hi:[1,0,1]
	v_pk_fma_f32 v[84:85], v[84:85], v[176:177], v[232:233] op_sel_hi:[1,0,1]
	v_pk_fma_f32 v[82:83], v[82:83], v[176:177], v[238:239] op_sel_hi:[1,0,1]
	v_pk_fma_f32 v[80:81], v[80:81], v[176:177], v[236:237] op_sel_hi:[1,0,1]
	v_max_f32_e32 v92, 0, v92
	v_max_f32_e32 v93, 0, v93
	v_max_f32_e32 v94, 0, v94
	v_max_f32_e32 v95, 0, v95
	v_max_f32_e32 v88, 0, v88
	v_max_f32_e32 v89, 0, v89
	v_max_f32_e32 v90, 0, v90
	v_max_f32_e32 v91, 0, v91
	v_mul_f32_e32 v92, v92, v92
	v_mul_f32_e32 v93, v93, v93
	v_mul_f32_e32 v94, v94, v94
	v_mul_f32_e32 v95, v95, v95
	v_mul_f32_e32 v88, v88, v88
	v_mul_f32_e32 v89, v89, v89
	v_mul_f32_e32 v90, v90, v90
	v_mul_f32_e32 v91, v91, v91
	v_cvt_pk_bf16_f32 v92, v92, v93
	v_cvt_pk_bf16_f32 v93, v94, v95
	v_cvt_pk_bf16_f32 v94, v88, v89
	v_cvt_pk_bf16_f32 v95, v90, v91
	global_store_dwordx4 v197, v[92:95], s[12:13]
	v_max_f32_e32 v84, 0, v84
	v_max_f32_e32 v85, 0, v85
	v_max_f32_e32 v86, 0, v86
	v_max_f32_e32 v87, 0, v87
	v_max_f32_e32 v80, 0, v80
	v_max_f32_e32 v81, 0, v81
	v_max_f32_e32 v82, 0, v82
	v_max_f32_e32 v83, 0, v83
	v_mul_f32_e32 v84, v84, v84
	v_mul_f32_e32 v85, v85, v85
	v_mul_f32_e32 v86, v86, v86
	v_mul_f32_e32 v87, v87, v87
	v_mul_f32_e32 v80, v80, v80
	v_mul_f32_e32 v81, v81, v81
	v_mul_f32_e32 v82, v82, v82
	v_mul_f32_e32 v83, v83, v83
	v_cvt_pk_bf16_f32 v84, v84, v85
	v_cvt_pk_bf16_f32 v85, v86, v87
	v_cvt_pk_bf16_f32 v86, v80, v81
	v_cvt_pk_bf16_f32 v87, v82, v83
	global_store_dwordx4 v197, v[84:87], s[12:13] offset:256
	v_add_u32_e32 v240, 0x20000, v197
	v_add_u32_e32 v170, 0x90, v182
	v_cmp_gt_i32_e32 vcc, s33, v170
	v_add_u32_e32 v167, s44, v170
	v_add_u32_e32 v168, s45, v170
	v_cndmask_b32_e32 v167, v167, v168, vcc
	v_cmp_gt_i32_e32 vcc, s90, v167
	v_add_u32_e32 v168, 0xffffc000, v167
	v_lshrrev_b32_e32 v168, 3, v168
	v_ashrrev_i32_e32 v169, 11, v167
	v_add_u32_e32 v168, 8, v168
	v_cndmask_b32_e32 v167, v168, v169, vcc
	v_lshl_add_u32 v171, v167, 14, v183
	global_load_dwordx4 v[224:227], v171, s[14:15]
	global_load_dwordx4 v[228:231], v171, s[14:15] offset:16
	global_load_dwordx4 v[232:235], v171, s[14:15] offset:512
	global_load_dwordx4 v[236:239], v171, s[14:15] offset:528
	s_waitcnt vmcnt(12)
	v_pk_fma_f32 v[78:79], v[78:79], v[176:177], v[106:107] op_sel:[0,1,0] op_sel_hi:[1,1,1]
	v_pk_fma_f32 v[76:77], v[76:77], v[176:177], v[104:105] op_sel:[0,1,0] op_sel_hi:[1,1,1]
	v_pk_fma_f32 v[74:75], v[74:75], v[176:177], v[114:115] op_sel:[0,1,0] op_sel_hi:[1,1,1]
	v_pk_fma_f32 v[72:73], v[72:73], v[176:177], v[112:113] op_sel:[0,1,0] op_sel_hi:[1,1,1]
	v_pk_fma_f32 v[70:71], v[70:71], v[176:177], v[126:127] op_sel:[0,1,0] op_sel_hi:[1,1,1]
	v_pk_fma_f32 v[68:69], v[68:69], v[176:177], v[124:125] op_sel:[0,1,0] op_sel_hi:[1,1,1]
	v_pk_fma_f32 v[66:67], v[66:67], v[176:177], v[122:123] op_sel:[0,1,0] op_sel_hi:[1,1,1]
	v_pk_fma_f32 v[64:65], v[64:65], v[176:177], v[120:121] op_sel:[0,1,0] op_sel_hi:[1,1,1]
	v_max_f32_e32 v76, 0, v76
	v_max_f32_e32 v77, 0, v77
	v_max_f32_e32 v78, 0, v78
	v_max_f32_e32 v79, 0, v79
	v_max_f32_e32 v72, 0, v72
	v_max_f32_e32 v73, 0, v73
	v_max_f32_e32 v74, 0, v74
	v_max_f32_e32 v75, 0, v75
	v_mul_f32_e32 v76, v76, v76
	v_mul_f32_e32 v77, v77, v77
	v_mul_f32_e32 v78, v78, v78
	v_mul_f32_e32 v79, v79, v79
	v_mul_f32_e32 v72, v72, v72
	v_mul_f32_e32 v73, v73, v73
	v_mul_f32_e32 v74, v74, v74
	v_mul_f32_e32 v75, v75, v75
	v_cvt_pk_bf16_f32 v76, v76, v77
	v_cvt_pk_bf16_f32 v77, v78, v79
	v_cvt_pk_bf16_f32 v78, v72, v73
	v_cvt_pk_bf16_f32 v79, v74, v75
	global_store_dwordx4 v240, v[76:79], s[12:13]
	v_max_f32_e32 v68, 0, v68
	v_max_f32_e32 v69, 0, v69
	v_max_f32_e32 v70, 0, v70
	v_max_f32_e32 v71, 0, v71
	v_max_f32_e32 v64, 0, v64
	v_max_f32_e32 v65, 0, v65
	v_max_f32_e32 v66, 0, v66
	v_max_f32_e32 v67, 0, v67
	v_mul_f32_e32 v68, v68, v68
	v_mul_f32_e32 v69, v69, v69
	v_mul_f32_e32 v70, v70, v70
	v_mul_f32_e32 v71, v71, v71
	v_mul_f32_e32 v64, v64, v64
	v_mul_f32_e32 v65, v65, v65
	v_mul_f32_e32 v66, v66, v66
	v_mul_f32_e32 v67, v67, v67
	v_cvt_pk_bf16_f32 v68, v68, v69
	v_cvt_pk_bf16_f32 v69, v70, v71
	v_cvt_pk_bf16_f32 v70, v64, v65
	v_cvt_pk_bf16_f32 v71, v66, v67
	global_store_dwordx4 v240, v[68:71], s[12:13] offset:256
	v_add_u32_e32 v197, 0xa0000, v240
	v_add_u32_e32 v170, 0xa0, v182
	v_cmp_gt_i32_e32 vcc, s33, v170
	v_add_u32_e32 v167, s44, v170
	v_add_u32_e32 v168, s45, v170
	v_cndmask_b32_e32 v167, v167, v168, vcc
	v_cmp_gt_i32_e32 vcc, s90, v167
	v_add_u32_e32 v168, 0xffffc000, v167
	v_lshrrev_b32_e32 v168, 3, v168
	v_ashrrev_i32_e32 v169, 11, v167
	v_add_u32_e32 v168, 8, v168
	v_cndmask_b32_e32 v167, v168, v169, vcc
	v_lshl_add_u32 v171, v167, 14, v183
	global_load_dwordx4 v[104:107], v171, s[14:15]
	global_load_dwordx4 v[112:115], v171, s[14:15] offset:16
	global_load_dwordx4 v[124:127], v171, s[14:15] offset:512
	global_load_dwordx4 v[120:123], v171, s[14:15] offset:528
	s_waitcnt vmcnt(12)
	v_pk_fma_f32 v[62:63], v[62:63], v[178:179], v[200:201] op_sel_hi:[1,0,1]
	v_pk_fma_f32 v[60:61], v[60:61], v[178:179], v[198:199] op_sel_hi:[1,0,1]
	v_pk_fma_f32 v[58:59], v[58:59], v[178:179], v[204:205] op_sel_hi:[1,0,1]
	v_pk_fma_f32 v[56:57], v[56:57], v[178:179], v[202:203] op_sel_hi:[1,0,1]
	v_pk_fma_f32 v[54:55], v[54:55], v[178:179], v[208:209] op_sel_hi:[1,0,1]
	v_pk_fma_f32 v[52:53], v[52:53], v[178:179], v[206:207] op_sel_hi:[1,0,1]
	v_pk_fma_f32 v[50:51], v[50:51], v[178:179], v[212:213] op_sel_hi:[1,0,1]
	v_pk_fma_f32 v[48:49], v[48:49], v[178:179], v[210:211] op_sel_hi:[1,0,1]
	v_max_f32_e32 v60, 0, v60
	v_max_f32_e32 v61, 0, v61
	v_max_f32_e32 v62, 0, v62
	v_max_f32_e32 v63, 0, v63
	v_max_f32_e32 v56, 0, v56
	v_max_f32_e32 v57, 0, v57
	v_max_f32_e32 v58, 0, v58
	v_max_f32_e32 v59, 0, v59
	v_mul_f32_e32 v60, v60, v60
	v_mul_f32_e32 v61, v61, v61
	v_mul_f32_e32 v62, v62, v62
	v_mul_f32_e32 v63, v63, v63
	v_mul_f32_e32 v56, v56, v56
	v_mul_f32_e32 v57, v57, v57
	v_mul_f32_e32 v58, v58, v58
	v_mul_f32_e32 v59, v59, v59
	v_cvt_pk_bf16_f32 v60, v60, v61
	v_cvt_pk_bf16_f32 v61, v62, v63
	v_cvt_pk_bf16_f32 v62, v56, v57
	v_cvt_pk_bf16_f32 v63, v58, v59
	global_store_dwordx4 v197, v[60:63], s[12:13]
	v_max_f32_e32 v52, 0, v52
	v_max_f32_e32 v53, 0, v53
	v_max_f32_e32 v54, 0, v54
	v_max_f32_e32 v55, 0, v55
	v_max_f32_e32 v48, 0, v48
	v_max_f32_e32 v49, 0, v49
	v_max_f32_e32 v50, 0, v50
	v_max_f32_e32 v51, 0, v51
	v_mul_f32_e32 v52, v52, v52
	v_mul_f32_e32 v53, v53, v53
	v_mul_f32_e32 v54, v54, v54
	v_mul_f32_e32 v55, v55, v55
	v_mul_f32_e32 v48, v48, v48
	v_mul_f32_e32 v49, v49, v49
	v_mul_f32_e32 v50, v50, v50
	v_mul_f32_e32 v51, v51, v51
	v_cvt_pk_bf16_f32 v52, v52, v53
	v_cvt_pk_bf16_f32 v53, v54, v55
	v_cvt_pk_bf16_f32 v54, v48, v49
	v_cvt_pk_bf16_f32 v55, v50, v51
	global_store_dwordx4 v197, v[52:55], s[12:13] offset:256
	v_add_u32_e32 v240, 0x20000, v197
	v_add_u32_e32 v170, 0xb0, v182
	v_cmp_gt_i32_e32 vcc, s33, v170
	v_add_u32_e32 v167, s44, v170
	v_add_u32_e32 v168, s45, v170
	v_cndmask_b32_e32 v167, v167, v168, vcc
	v_cmp_gt_i32_e32 vcc, s90, v167
	v_add_u32_e32 v168, 0xffffc000, v167
	v_lshrrev_b32_e32 v168, 3, v168
	v_ashrrev_i32_e32 v169, 11, v167
	v_add_u32_e32 v168, 8, v168
	v_cndmask_b32_e32 v167, v168, v169, vcc
	v_lshl_add_u32 v171, v167, 14, v183
	global_load_dwordx4 v[198:201], v171, s[14:15]
	global_load_dwordx4 v[202:205], v171, s[14:15] offset:16
	global_load_dwordx4 v[206:209], v171, s[14:15] offset:512
	global_load_dwordx4 v[210:213], v171, s[14:15] offset:528
	s_waitcnt vmcnt(12)
	v_pk_fma_f32 v[46:47], v[46:47], v[178:179], v[226:227] op_sel:[0,1,0] op_sel_hi:[1,1,1]
	v_pk_fma_f32 v[44:45], v[44:45], v[178:179], v[224:225] op_sel:[0,1,0] op_sel_hi:[1,1,1]
	v_pk_fma_f32 v[42:43], v[42:43], v[178:179], v[230:231] op_sel:[0,1,0] op_sel_hi:[1,1,1]
	v_pk_fma_f32 v[40:41], v[40:41], v[178:179], v[228:229] op_sel:[0,1,0] op_sel_hi:[1,1,1]
	v_pk_fma_f32 v[38:39], v[38:39], v[178:179], v[234:235] op_sel:[0,1,0] op_sel_hi:[1,1,1]
	v_pk_fma_f32 v[36:37], v[36:37], v[178:179], v[232:233] op_sel:[0,1,0] op_sel_hi:[1,1,1]
	v_pk_fma_f32 v[34:35], v[34:35], v[178:179], v[238:239] op_sel:[0,1,0] op_sel_hi:[1,1,1]
	v_pk_fma_f32 v[32:33], v[32:33], v[178:179], v[236:237] op_sel:[0,1,0] op_sel_hi:[1,1,1]
	v_max_f32_e32 v44, 0, v44
	v_max_f32_e32 v45, 0, v45
	v_max_f32_e32 v46, 0, v46
	v_max_f32_e32 v47, 0, v47
	v_max_f32_e32 v40, 0, v40
	v_max_f32_e32 v41, 0, v41
	v_max_f32_e32 v42, 0, v42
	v_max_f32_e32 v43, 0, v43
	v_mul_f32_e32 v44, v44, v44
	v_mul_f32_e32 v45, v45, v45
	v_mul_f32_e32 v46, v46, v46
	v_mul_f32_e32 v47, v47, v47
	v_mul_f32_e32 v40, v40, v40
	v_mul_f32_e32 v41, v41, v41
	v_mul_f32_e32 v42, v42, v42
	v_mul_f32_e32 v43, v43, v43
	v_cvt_pk_bf16_f32 v44, v44, v45
	v_cvt_pk_bf16_f32 v45, v46, v47
	v_cvt_pk_bf16_f32 v46, v40, v41
	v_cvt_pk_bf16_f32 v47, v42, v43
	global_store_dwordx4 v240, v[44:47], s[12:13]
	v_max_f32_e32 v36, 0, v36
	v_max_f32_e32 v37, 0, v37
	v_max_f32_e32 v38, 0, v38
	v_max_f32_e32 v39, 0, v39
	v_max_f32_e32 v32, 0, v32
	v_max_f32_e32 v33, 0, v33
	v_max_f32_e32 v34, 0, v34
	v_max_f32_e32 v35, 0, v35
	v_mul_f32_e32 v36, v36, v36
	v_mul_f32_e32 v37, v37, v37
	v_mul_f32_e32 v38, v38, v38
	v_mul_f32_e32 v39, v39, v39
	v_mul_f32_e32 v32, v32, v32
	v_mul_f32_e32 v33, v33, v33
	v_mul_f32_e32 v34, v34, v34
	v_mul_f32_e32 v35, v35, v35
	v_cvt_pk_bf16_f32 v36, v36, v37
	v_cvt_pk_bf16_f32 v37, v38, v39
	v_cvt_pk_bf16_f32 v38, v32, v33
	v_cvt_pk_bf16_f32 v39, v34, v35
	global_store_dwordx4 v240, v[36:39], s[12:13] offset:256
	v_add_u32_e32 v197, 0x20000, v240
	s_waitcnt vmcnt(8)
	v_pk_fma_f32 v[30:31], v[30:31], v[180:181], v[106:107] op_sel_hi:[1,0,1]
	v_pk_fma_f32 v[28:29], v[28:29], v[180:181], v[104:105] op_sel_hi:[1,0,1]
	v_pk_fma_f32 v[26:27], v[26:27], v[180:181], v[114:115] op_sel_hi:[1,0,1]
	v_pk_fma_f32 v[24:25], v[24:25], v[180:181], v[112:113] op_sel_hi:[1,0,1]
	v_pk_fma_f32 v[22:23], v[22:23], v[180:181], v[126:127] op_sel_hi:[1,0,1]
	v_pk_fma_f32 v[20:21], v[20:21], v[180:181], v[124:125] op_sel_hi:[1,0,1]
	v_pk_fma_f32 v[18:19], v[18:19], v[180:181], v[122:123] op_sel_hi:[1,0,1]
	v_pk_fma_f32 v[16:17], v[16:17], v[180:181], v[120:121] op_sel_hi:[1,0,1]
	v_max_f32_e32 v28, 0, v28
	v_max_f32_e32 v29, 0, v29
	v_max_f32_e32 v30, 0, v30
	v_max_f32_e32 v31, 0, v31
	v_max_f32_e32 v24, 0, v24
	v_max_f32_e32 v25, 0, v25
	v_max_f32_e32 v26, 0, v26
	v_max_f32_e32 v27, 0, v27
	v_mul_f32_e32 v28, v28, v28
	v_mul_f32_e32 v29, v29, v29
	v_mul_f32_e32 v30, v30, v30
	v_mul_f32_e32 v31, v31, v31
	v_mul_f32_e32 v24, v24, v24
	v_mul_f32_e32 v25, v25, v25
	v_mul_f32_e32 v26, v26, v26
	v_mul_f32_e32 v27, v27, v27
	v_cvt_pk_bf16_f32 v28, v28, v29
	v_cvt_pk_bf16_f32 v29, v30, v31
	v_cvt_pk_bf16_f32 v30, v24, v25
	v_cvt_pk_bf16_f32 v31, v26, v27
	global_store_dwordx4 v197, v[28:31], s[12:13]
	v_max_f32_e32 v20, 0, v20
	v_max_f32_e32 v21, 0, v21
	v_max_f32_e32 v22, 0, v22
	v_max_f32_e32 v23, 0, v23
	v_max_f32_e32 v16, 0, v16
	v_max_f32_e32 v17, 0, v17
	v_max_f32_e32 v18, 0, v18
	v_max_f32_e32 v19, 0, v19
	v_mul_f32_e32 v20, v20, v20
	v_mul_f32_e32 v21, v21, v21
	v_mul_f32_e32 v22, v22, v22
	v_mul_f32_e32 v23, v23, v23
	v_mul_f32_e32 v16, v16, v16
	v_mul_f32_e32 v17, v17, v17
	v_mul_f32_e32 v18, v18, v18
	v_mul_f32_e32 v19, v19, v19
	v_cvt_pk_bf16_f32 v20, v20, v21
	v_cvt_pk_bf16_f32 v21, v22, v23
	v_cvt_pk_bf16_f32 v22, v16, v17
	v_cvt_pk_bf16_f32 v23, v18, v19
	global_store_dwordx4 v197, v[20:23], s[12:13] offset:256
	v_add_u32_e32 v240, 0x20000, v197
	s_waitcnt vmcnt(4)
	v_pk_fma_f32 v[14:15], v[14:15], v[180:181], v[200:201] op_sel:[0,1,0] op_sel_hi:[1,1,1]
	v_pk_fma_f32 v[12:13], v[12:13], v[180:181], v[198:199] op_sel:[0,1,0] op_sel_hi:[1,1,1]
	v_pk_fma_f32 v[10:11], v[10:11], v[180:181], v[204:205] op_sel:[0,1,0] op_sel_hi:[1,1,1]
	v_pk_fma_f32 v[8:9], v[8:9], v[180:181], v[202:203] op_sel:[0,1,0] op_sel_hi:[1,1,1]
	v_pk_fma_f32 v[6:7], v[6:7], v[180:181], v[208:209] op_sel:[0,1,0] op_sel_hi:[1,1,1]
	v_pk_fma_f32 v[4:5], v[4:5], v[180:181], v[206:207] op_sel:[0,1,0] op_sel_hi:[1,1,1]
	v_pk_fma_f32 v[2:3], v[2:3], v[180:181], v[212:213] op_sel:[0,1,0] op_sel_hi:[1,1,1]
	v_pk_fma_f32 v[0:1], v[0:1], v[180:181], v[210:211] op_sel:[0,1,0] op_sel_hi:[1,1,1]
	v_max_f32_e32 v12, 0, v12
	v_max_f32_e32 v13, 0, v13
	v_max_f32_e32 v14, 0, v14
	v_max_f32_e32 v15, 0, v15
	v_max_f32_e32 v8, 0, v8
	v_max_f32_e32 v9, 0, v9
	v_max_f32_e32 v10, 0, v10
	v_max_f32_e32 v11, 0, v11
	v_mul_f32_e32 v12, v12, v12
	v_mul_f32_e32 v13, v13, v13
	v_mul_f32_e32 v14, v14, v14
	v_mul_f32_e32 v15, v15, v15
	v_mul_f32_e32 v8, v8, v8
	v_mul_f32_e32 v9, v9, v9
	v_mul_f32_e32 v10, v10, v10
	v_mul_f32_e32 v11, v11, v11
	v_cvt_pk_bf16_f32 v12, v12, v13
	v_cvt_pk_bf16_f32 v13, v14, v15
	v_cvt_pk_bf16_f32 v14, v8, v9
	v_cvt_pk_bf16_f32 v15, v10, v11
	global_store_dwordx4 v240, v[12:15], s[12:13]
	v_max_f32_e32 v4, 0, v4
	v_max_f32_e32 v5, 0, v5
	v_max_f32_e32 v6, 0, v6
	v_max_f32_e32 v7, 0, v7
	v_max_f32_e32 v0, 0, v0
	v_max_f32_e32 v1, 0, v1
	v_max_f32_e32 v2, 0, v2
	v_max_f32_e32 v3, 0, v3
	v_mul_f32_e32 v4, v4, v4
	v_mul_f32_e32 v5, v5, v5
	v_mul_f32_e32 v6, v6, v6
	v_mul_f32_e32 v7, v7, v7
	v_mul_f32_e32 v0, v0, v0
	v_mul_f32_e32 v1, v1, v1
	v_mul_f32_e32 v2, v2, v2
	v_mul_f32_e32 v3, v3, v3
	v_cvt_pk_bf16_f32 v4, v4, v5
	v_cvt_pk_bf16_f32 v5, v6, v7
	v_cvt_pk_bf16_f32 v6, v0, v1
	v_cvt_pk_bf16_f32 v7, v2, v3
	global_store_dwordx4 v240, v[4:7], s[12:13] offset:256
	s_andn2_b64 vcc, exec, s[18:19]
	s_mov_b64 s[18:19], -1
	s_cbranch_vccnz .LBB0_1222
	s_andn2_b64 vcc, exec, s[10:11]
	s_cbranch_vccnz .LBB0_1221
	s_barrier
	s_branch .LBB0_1221
